# v27 plus: barrier leaders no longer write the unused per-XCD relay word nor wait for their last barrier atomic before leaving
# baseline (speedup 1.0000x reference)
; __device__ __forceinline__ unsigned xb_ld(unsigned* p)              { return __hip_atomic_load(p, __ATOMIC_RELAXED, __HIP_MEMORY_SCOPE_AGENT); }
; __device__ __forceinline__ unsigned xb_add(unsigned* p, unsigned v) { return __hip_atomic_fetch_add(p, v, __ATOMIC_RELAXED, __HIP_MEMORY_SCOPE_AGENT); }
; #define XB_SPIN(cond, bar) do { unsigned _sp = 0; while (cond) { __builtin_amdgcn_s_sleep(1); \
;     if ((++_sp & 255u) == 0u) { if (xb_ld(&(bar)[XB_TMO])) break; if (_sp > XB_SPIN_CAP) { atomicAdd(&(bar)[XB_TMO], 1u); break; } } } } while (0)
; __device__ __forceinline__ void xcd_barrier(const XcdBarrier& b) {
;     ...
;         const unsigned old = xb_add(&bar[XB_XSUB(b.x)], 1u);
;         const unsigned gen = old / nloc;
;         if (old + 1u == (gen + 1u) * nloc) {
;             __builtin_amdgcn_fence(__ATOMIC_RELEASE, "agent");
;             asm volatile("s_waitcnt vmcnt(0)" ::: "memory");
;             const unsigned og = xb_add(&bar[XB_TOP], 1u);
;             const unsigned tg = og / nx;
;             if (og + 1u == (tg + 1u) * nx) xb_add(&bar[XB_TOPGEN], 1u);
;             else XB_SPIN(xb_ld(&bar[XB_TOPGEN]) == tg, bar);
;             __builtin_amdgcn_fence(__ATOMIC_ACQUIRE, "agent");
;             xb_add(&bar[XB_XGEN(b.x)], 1u);
;             asm volatile("s_waitcnt vmcnt(0)" ::: "memory");
;         } else {
.LBB0_101:
	s_or_b64 exec, exec, s[12:13]
	s_mov_b64 s[6:7], exec
	v_mbcnt_lo_u32_b32 v0, s6, 0
	v_mbcnt_hi_u32_b32 v0, s7, v0
	v_cmp_eq_u32_e32 vcc, 0, v0
	s_and_saveexec_b64 s[12:13], vcc
	s_cbranch_execz .LBB0_103
	s_bcnt1_i32_b64 s6, s[6:7]
	v_mov_b32_e32 v0, 0x2000
	v_mov_b32_e32 v1, s6
.LBB0_103:
	s_or_b64 exec, exec, s[12:13]
.LBB0_104:
	s_or_b64 exec, exec, s[0:1]
	s_waitcnt lgkmcnt(0)
	s_barrier

; __device__ __forceinline__ unsigned xb_ld(unsigned* p)              { return __hip_atomic_load(p, __ATOMIC_RELAXED, __HIP_MEMORY_SCOPE_AGENT); }
; __device__ __forceinline__ unsigned xb_add(unsigned* p, unsigned v) { return __hip_atomic_fetch_add(p, v, __ATOMIC_RELAXED, __HIP_MEMORY_SCOPE_AGENT); }
; #define XB_SPIN(cond, bar) do { unsigned _sp = 0; while (cond) { __builtin_amdgcn_s_sleep(1); \
;     if ((++_sp & 255u) == 0u) { if (xb_ld(&(bar)[XB_TMO])) break; if (_sp > XB_SPIN_CAP) { atomicAdd(&(bar)[XB_TMO], 1u); break; } } } } while (0)
; __device__ __forceinline__ void xcd_barrier(const XcdBarrier& b) {
;     ...
;         const unsigned old = xb_add(&bar[XB_XSUB(b.x)], 1u);
;         const unsigned gen = old / nloc;
;         if (old + 1u == (gen + 1u) * nloc) {
;             __builtin_amdgcn_fence(__ATOMIC_RELEASE, "agent");
;             asm volatile("s_waitcnt vmcnt(0)" ::: "memory");
;             const unsigned og = xb_add(&bar[XB_TOP], 1u);
;             const unsigned tg = og / nx;
;             if (og + 1u == (tg + 1u) * nx) xb_add(&bar[XB_TOPGEN], 1u);
;             else XB_SPIN(xb_ld(&bar[XB_TOPGEN]) == tg, bar);
;             __builtin_amdgcn_fence(__ATOMIC_ACQUIRE, "agent");
;             xb_add(&bar[XB_XGEN(b.x)], 1u);
;             asm volatile("s_waitcnt vmcnt(0)" ::: "memory");
;         } else {
.LBB0_294:
	s_or_b64 exec, exec, s[12:13]
.LBB0_295:
	s_or_b64 exec, exec, s[4:5]
	s_waitcnt lgkmcnt(0)
	s_barrier

; __device__ __forceinline__ unsigned xb_ld(unsigned* p)              { return __hip_atomic_load(p, __ATOMIC_RELAXED, __HIP_MEMORY_SCOPE_AGENT); }
; __device__ __forceinline__ unsigned xb_add(unsigned* p, unsigned v) { return __hip_atomic_fetch_add(p, v, __ATOMIC_RELAXED, __HIP_MEMORY_SCOPE_AGENT); }
; #define XB_SPIN(cond, bar) do { unsigned _sp = 0; while (cond) { __builtin_amdgcn_s_sleep(1); \
;     if ((++_sp & 255u) == 0u) { if (xb_ld(&(bar)[XB_TMO])) break; if (_sp > XB_SPIN_CAP) { atomicAdd(&(bar)[XB_TMO], 1u); break; } } } } while (0)
; __device__ __forceinline__ void xcd_barrier(const XcdBarrier& b) {
;     ...
;         const unsigned old = xb_add(&bar[XB_XSUB(b.x)], 1u);
;         const unsigned gen = old / nloc;
;         if (old + 1u == (gen + 1u) * nloc) {
;             __builtin_amdgcn_fence(__ATOMIC_RELEASE, "agent");
;             asm volatile("s_waitcnt vmcnt(0)" ::: "memory");
;             const unsigned og = xb_add(&bar[XB_TOP], 1u);
;             const unsigned tg = og / nx;
;             if (og + 1u == (tg + 1u) * nx) xb_add(&bar[XB_TOPGEN], 1u);
;             else XB_SPIN(xb_ld(&bar[XB_TOPGEN]) == tg, bar);
;             __builtin_amdgcn_fence(__ATOMIC_ACQUIRE, "agent");
;             xb_add(&bar[XB_XGEN(b.x)], 1u);
;             asm volatile("s_waitcnt vmcnt(0)" ::: "memory");
;         } else {
.LBB0_490:
	s_or_b64 exec, exec, s[8:9]
	s_mov_b64 s[8:9], exec
	v_mbcnt_lo_u32_b32 v0, s8, 0
	v_mbcnt_hi_u32_b32 v0, s9, v0
	v_cmp_eq_u32_e32 vcc, 0, v0
	s_and_saveexec_b64 s[10:11], vcc
	s_cbranch_execz .LBB0_492
	s_bcnt1_i32_b64 s8, s[8:9]
	v_mov_b32_e32 v0, 0x2000
	v_mov_b32_e32 v1, s8
.LBB0_492:
	s_or_b64 exec, exec, s[10:11]
.LBB0_493:
	s_or_b64 exec, exec, s[4:5]
	s_waitcnt lgkmcnt(0)
	s_barrier

; __device__ __forceinline__ unsigned xb_ld(unsigned* p)              { return __hip_atomic_load(p, __ATOMIC_RELAXED, __HIP_MEMORY_SCOPE_AGENT); }
; __device__ __forceinline__ unsigned xb_add(unsigned* p, unsigned v) { return __hip_atomic_fetch_add(p, v, __ATOMIC_RELAXED, __HIP_MEMORY_SCOPE_AGENT); }
; #define XB_SPIN(cond, bar) do { unsigned _sp = 0; while (cond) { __builtin_amdgcn_s_sleep(1); \
;     if ((++_sp & 255u) == 0u) { if (xb_ld(&(bar)[XB_TMO])) break; if (_sp > XB_SPIN_CAP) { atomicAdd(&(bar)[XB_TMO], 1u); break; } } } } while (0)
; __device__ __forceinline__ void xcd_barrier(const XcdBarrier& b) {
;     ...
;         const unsigned old = xb_add(&bar[XB_XSUB(b.x)], 1u);
;         const unsigned gen = old / nloc;
;         if (old + 1u == (gen + 1u) * nloc) {
;             __builtin_amdgcn_fence(__ATOMIC_RELEASE, "agent");
;             asm volatile("s_waitcnt vmcnt(0)" ::: "memory");
;             const unsigned og = xb_add(&bar[XB_TOP], 1u);
;             const unsigned tg = og / nx;
;             if (og + 1u == (tg + 1u) * nx) xb_add(&bar[XB_TOPGEN], 1u);
;             else XB_SPIN(xb_ld(&bar[XB_TOPGEN]) == tg, bar);
;             __builtin_amdgcn_fence(__ATOMIC_ACQUIRE, "agent");
;             xb_add(&bar[XB_XGEN(b.x)], 1u);
;             asm volatile("s_waitcnt vmcnt(0)" ::: "memory");
;         } else {
.LBB0_579:
	s_or_b64 exec, exec, s[10:11]
.LBB0_580:
	s_or_b64 exec, exec, s[0:1]
	s_waitcnt lgkmcnt(0)
	s_barrier
